# v99 + GEMM main loops (.LBB0_385/417/480) pinned to 64B alignment
# baseline (speedup 1.0000x reference)
; template <class Epi, class Sched>
; __device__ __forceinline__ void gemm_phase(LAS unsigned char* lds, const Gemm g, const Sched& S, const Epi& E, const int tid) {
;     ...
;         const bool has_next = S.next(ui + 1, nxt);
;         const char* nA = has_next ? (const char*)g.A + (size_t)nxt.pm * tstep : cA; const char* nB = has_next ? (const char*)g.Bt + (size_t)nxt.pn * tstep : cB;
;         for (int t = 0; t < nt; t += 2) {
;             const bool last = (t == nt - 2);
;             const char* a1 = cA + (size_t)(t + 1) * kstep;
;             const char* a2 = last ? nA : cA + (size_t)(t + 2) * kstep; const char* b2 = last ? nB : cB + (size_t)(t + 2) * kstep;
;             const char* a3 = a2 + kstep; const char* b3 = b2 + kstep;
;     ...
; #pragma unroll
;         for (int a = 0; a < 2; ++a)
; #pragma unroll
;             for (int b = 0; b < 2; ++b)
; #pragma unroll
;                 for (int m = 0; m < 4; ++m)
; #pragma unroll
;                     for (int n = 0; n < 2; ++n) acc[a][b][m][n] = (f32x4){0.f, 0.f, 0.f, 0.f};
;         cur = nxt; cA = nA; cB = nB; ++ui;
.LBB0_384:
	s_add_u32 s71, s66, 0x100
	s_addc_u32 s84, s67, 0
	s_add_u32 s66, s68, 0x80
	v_mov_b32_e32 v2, 0
	s_addc_u32 s67, s69, 0
	s_mov_b32 s31, 0
	v_mov_b32_e32 v3, v2
	v_mov_b32_e32 v4, v2
	v_mov_b32_e32 v5, v2
	v_mov_b32_e32 v6, v2
	v_mov_b32_e32 v7, v2
	v_mov_b32_e32 v8, v2
	v_mov_b32_e32 v9, v2
	v_mov_b32_e32 v18, v2
	v_mov_b32_e32 v19, v2
	v_mov_b32_e32 v20, v2
	v_mov_b32_e32 v21, v2
	v_mov_b32_e32 v22, v2
	v_mov_b32_e32 v23, v2
	v_mov_b32_e32 v24, v2
	v_mov_b32_e32 v25, v2
	v_mov_b32_e32 v34, v2
	v_mov_b32_e32 v35, v2
	v_mov_b32_e32 v36, v2
	v_mov_b32_e32 v37, v2
	v_mov_b32_e32 v38, v2
	v_mov_b32_e32 v39, v2
	v_mov_b32_e32 v40, v2
	v_mov_b32_e32 v41, v2
	v_mov_b32_e32 v50, v2
	v_mov_b32_e32 v51, v2
	v_mov_b32_e32 v52, v2
	v_mov_b32_e32 v53, v2
	v_mov_b32_e32 v54, v2
	v_mov_b32_e32 v55, v2
	v_mov_b32_e32 v56, v2
	v_mov_b32_e32 v57, v2
	v_mov_b32_e32 v10, v2
	v_mov_b32_e32 v11, v2
	v_mov_b32_e32 v12, v2
	v_mov_b32_e32 v13, v2
	v_mov_b32_e32 v14, v2
	v_mov_b32_e32 v15, v2
	v_mov_b32_e32 v16, v2
	v_mov_b32_e32 v17, v2
	v_mov_b32_e32 v26, v2
	v_mov_b32_e32 v27, v2
	v_mov_b32_e32 v28, v2
	v_mov_b32_e32 v29, v2
	v_mov_b32_e32 v30, v2
	v_mov_b32_e32 v31, v2
	v_mov_b32_e32 v32, v2
	v_mov_b32_e32 v33, v2
	v_mov_b32_e32 v42, v2
	v_mov_b32_e32 v43, v2
	v_mov_b32_e32 v44, v2
	v_mov_b32_e32 v45, v2
	v_mov_b32_e32 v46, v2
	v_mov_b32_e32 v47, v2
	v_mov_b32_e32 v48, v2
	v_mov_b32_e32 v49, v2
	v_mov_b32_e32 v58, v2
	v_mov_b32_e32 v59, v2
	v_mov_b32_e32 v60, v2
	v_mov_b32_e32 v61, v2
	v_mov_b32_e32 v62, v2
	v_mov_b32_e32 v63, v2
	v_mov_b32_e32 v64, v2
	v_mov_b32_e32 v65, v2
	v_mov_b32_e32 v66, v2
	v_mov_b32_e32 v67, v2
	v_mov_b32_e32 v68, v2
	v_mov_b32_e32 v69, v2
	v_mov_b32_e32 v70, v2
	v_mov_b32_e32 v71, v2
	v_mov_b32_e32 v72, v2
	v_mov_b32_e32 v73, v2
	v_mov_b32_e32 v82, v2
	v_mov_b32_e32 v83, v2
	v_mov_b32_e32 v84, v2
	v_mov_b32_e32 v85, v2
	v_mov_b32_e32 v86, v2
	v_mov_b32_e32 v87, v2
	v_mov_b32_e32 v88, v2
	v_mov_b32_e32 v89, v2
	v_mov_b32_e32 v98, v2
	v_mov_b32_e32 v99, v2
	v_mov_b32_e32 v100, v2
	v_mov_b32_e32 v101, v2
	v_mov_b32_e32 v102, v2
	v_mov_b32_e32 v103, v2
	v_mov_b32_e32 v104, v2
	v_mov_b32_e32 v105, v2
	v_mov_b32_e32 v114, v2
	v_mov_b32_e32 v115, v2
	v_mov_b32_e32 v116, v2
	v_mov_b32_e32 v117, v2
	v_mov_b32_e32 v118, v2
	v_mov_b32_e32 v119, v2
	v_mov_b32_e32 v120, v2
	v_mov_b32_e32 v121, v2
	v_mov_b32_e32 v74, v2
	v_mov_b32_e32 v75, v2
	v_mov_b32_e32 v76, v2
	v_mov_b32_e32 v77, v2
	v_mov_b32_e32 v78, v2
	v_mov_b32_e32 v79, v2
	v_mov_b32_e32 v80, v2
	v_mov_b32_e32 v81, v2
	v_mov_b32_e32 v90, v2
	v_mov_b32_e32 v91, v2
	v_mov_b32_e32 v92, v2
	v_mov_b32_e32 v93, v2
	v_mov_b32_e32 v94, v2
	v_mov_b32_e32 v95, v2
	v_mov_b32_e32 v96, v2
	v_mov_b32_e32 v97, v2
	v_mov_b32_e32 v106, v2
	v_mov_b32_e32 v107, v2
	v_mov_b32_e32 v108, v2
	v_mov_b32_e32 v109, v2
	v_mov_b32_e32 v110, v2
	v_mov_b32_e32 v111, v2
	v_mov_b32_e32 v112, v2
	v_mov_b32_e32 v113, v2
	v_mov_b32_e32 v122, v2
	v_mov_b32_e32 v123, v2
	v_mov_b32_e32 v124, v2
	v_mov_b32_e32 v125, v2
	v_mov_b32_e32 v126, v2
	v_mov_b32_e32 v127, v2
	v_mov_b32_e32 v128, v2
	v_mov_b32_e32 v129, v2
	.p2align 6

; template <class Epi, class Sched>
; __device__ __forceinline__ void gemm_phase(LAS unsigned char* lds, const Gemm g, const Sched& S, const Epi& E, const int tid) {
;     ...
;         const bool has_next = S.next(ui + 1, nxt);
;         const char* nA = has_next ? (const char*)g.A + (size_t)nxt.pm * tstep : cA; const char* nB = has_next ? (const char*)g.Bt + (size_t)nxt.pn * tstep : cB;
;         for (int t = 0; t < nt; t += 2) {
;             const bool last = (t == nt - 2);
;             const char* a1 = cA + (size_t)(t + 1) * kstep;
;             const char* a2 = last ? nA : cA + (size_t)(t + 2) * kstep; const char* b2 = last ? nB : cB + (size_t)(t + 2) * kstep;
;             const char* a3 = a2 + kstep; const char* b3 = b2 + kstep;
;     ...
; #pragma unroll
;         for (int a = 0; a < 2; ++a)
; #pragma unroll
;             for (int b = 0; b < 2; ++b)
; #pragma unroll
;                 for (int m = 0; m < 4; ++m)
; #pragma unroll
;                     for (int n = 0; n < 2; ++n) acc[a][b][m][n] = (f32x4){0.f, 0.f, 0.f, 0.f};
;         cur = nxt; cA = nA; cB = nB; ++ui;
.LBB0_416:
	s_add_u32 s98, s94, 0x100
	s_addc_u32 s99, s95, 0
	s_add_u32 s0, s96, 0x80
	v_mov_b32_e32 v6, 0
	s_addc_u32 s1, s97, 0
	s_mov_b32 s31, 0
	v_mov_b32_e32 v7, v6
	v_mov_b32_e32 v8, v6
	v_mov_b32_e32 v9, v6
	v_mov_b32_e32 v2, v6
	v_mov_b32_e32 v3, v6
	v_mov_b32_e32 v4, v6
	v_mov_b32_e32 v5, v6
	v_mov_b32_e32 v22, v6
	v_mov_b32_e32 v23, v6
	v_mov_b32_e32 v24, v6
	v_mov_b32_e32 v25, v6
	v_mov_b32_e32 v18, v6
	v_mov_b32_e32 v19, v6
	v_mov_b32_e32 v20, v6
	v_mov_b32_e32 v21, v6
	v_mov_b32_e32 v38, v6
	v_mov_b32_e32 v39, v6
	v_mov_b32_e32 v40, v6
	v_mov_b32_e32 v41, v6
	v_mov_b32_e32 v34, v6
	v_mov_b32_e32 v35, v6
	v_mov_b32_e32 v36, v6
	v_mov_b32_e32 v37, v6
	v_mov_b32_e32 v54, v6
	v_mov_b32_e32 v55, v6
	v_mov_b32_e32 v56, v6
	v_mov_b32_e32 v57, v6
	v_mov_b32_e32 v50, v6
	v_mov_b32_e32 v51, v6
	v_mov_b32_e32 v52, v6
	v_mov_b32_e32 v53, v6
	v_mov_b32_e32 v10, v6
	v_mov_b32_e32 v11, v6
	v_mov_b32_e32 v12, v6
	v_mov_b32_e32 v13, v6
	v_mov_b32_e32 v14, v6
	v_mov_b32_e32 v15, v6
	v_mov_b32_e32 v16, v6
	v_mov_b32_e32 v17, v6
	v_mov_b32_e32 v26, v6
	v_mov_b32_e32 v27, v6
	v_mov_b32_e32 v28, v6
	v_mov_b32_e32 v29, v6
	v_mov_b32_e32 v30, v6
	v_mov_b32_e32 v31, v6
	v_mov_b32_e32 v32, v6
	v_mov_b32_e32 v33, v6
	v_mov_b32_e32 v42, v6
	v_mov_b32_e32 v43, v6
	v_mov_b32_e32 v44, v6
	v_mov_b32_e32 v45, v6
	v_mov_b32_e32 v46, v6
	v_mov_b32_e32 v47, v6
	v_mov_b32_e32 v48, v6
	v_mov_b32_e32 v49, v6
	v_mov_b32_e32 v58, v6
	v_mov_b32_e32 v59, v6
	v_mov_b32_e32 v60, v6
	v_mov_b32_e32 v61, v6
	v_mov_b32_e32 v62, v6
	v_mov_b32_e32 v63, v6
	v_mov_b32_e32 v64, v6
	v_mov_b32_e32 v65, v6
	v_mov_b32_e32 v70, v6
	v_mov_b32_e32 v71, v6
	v_mov_b32_e32 v72, v6
	v_mov_b32_e32 v73, v6
	v_mov_b32_e32 v66, v6
	v_mov_b32_e32 v67, v6
	v_mov_b32_e32 v68, v6
	v_mov_b32_e32 v69, v6
	v_mov_b32_e32 v86, v6
	v_mov_b32_e32 v87, v6
	v_mov_b32_e32 v88, v6
	v_mov_b32_e32 v89, v6
	v_mov_b32_e32 v82, v6
	v_mov_b32_e32 v83, v6
	v_mov_b32_e32 v84, v6
	v_mov_b32_e32 v85, v6
	v_mov_b32_e32 v102, v6
	v_mov_b32_e32 v103, v6
	v_mov_b32_e32 v104, v6
	v_mov_b32_e32 v105, v6
	v_mov_b32_e32 v98, v6
	v_mov_b32_e32 v99, v6
	v_mov_b32_e32 v100, v6
	v_mov_b32_e32 v101, v6
	v_mov_b32_e32 v118, v6
	v_mov_b32_e32 v119, v6
	v_mov_b32_e32 v120, v6
	v_mov_b32_e32 v121, v6
	v_mov_b32_e32 v114, v6
	v_mov_b32_e32 v115, v6
	v_mov_b32_e32 v116, v6
	v_mov_b32_e32 v117, v6
	v_mov_b32_e32 v74, v6
	v_mov_b32_e32 v75, v6
	v_mov_b32_e32 v76, v6
	v_mov_b32_e32 v77, v6
	v_mov_b32_e32 v78, v6
	v_mov_b32_e32 v79, v6
	v_mov_b32_e32 v80, v6
	v_mov_b32_e32 v81, v6
	v_mov_b32_e32 v90, v6
	v_mov_b32_e32 v91, v6
	v_mov_b32_e32 v92, v6
	v_mov_b32_e32 v93, v6
	v_mov_b32_e32 v94, v6
	v_mov_b32_e32 v95, v6
	v_mov_b32_e32 v96, v6
	v_mov_b32_e32 v97, v6
	v_mov_b32_e32 v106, v6
	v_mov_b32_e32 v107, v6
	v_mov_b32_e32 v108, v6
	v_mov_b32_e32 v109, v6
	v_mov_b32_e32 v110, v6
	v_mov_b32_e32 v111, v6
	v_mov_b32_e32 v112, v6
	v_mov_b32_e32 v113, v6
	v_mov_b32_e32 v122, v6
	v_mov_b32_e32 v123, v6
	v_mov_b32_e32 v124, v6
	v_mov_b32_e32 v125, v6
	v_mov_b32_e32 v126, v6
	v_mov_b32_e32 v127, v6
	v_mov_b32_e32 v128, v6
	v_mov_b32_e32 v129, v6
	.p2align 6

; template <class Epi, class Sched>
; __device__ __forceinline__ void gemm_phase(LAS unsigned char* lds, const Gemm g, const Sched& S, const Epi& E, const int tid) {
;     ...
;         const bool has_next = S.next(ui + 1, nxt);
;         const char* nA = has_next ? (const char*)g.A + (size_t)nxt.pm * tstep : cA; const char* nB = has_next ? (const char*)g.Bt + (size_t)nxt.pn * tstep : cB;
;         for (int t = 0; t < nt; t += 2) {
;             const bool last = (t == nt - 2);
;             const char* a1 = cA + (size_t)(t + 1) * kstep;
;             const char* a2 = last ? nA : cA + (size_t)(t + 2) * kstep; const char* b2 = last ? nB : cB + (size_t)(t + 2) * kstep;
;             const char* a3 = a2 + kstep; const char* b3 = b2 + kstep;
;     ...
; #pragma unroll
;         for (int a = 0; a < 2; ++a)
; #pragma unroll
;             for (int b = 0; b < 2; ++b)
; #pragma unroll
;                 for (int m = 0; m < 4; ++m)
; #pragma unroll
;                     for (int n = 0; n < 2; ++n) acc[a][b][m][n] = (f32x4){0.f, 0.f, 0.f, 0.f};
;         cur = nxt; cA = nA; cB = nB; ++ui;
.LBB0_479:
	s_add_u32 s42, s62, 0x100
	s_addc_u32 s43, s63, 0
	s_add_u32 s62, s64, 0x80
	v_mov_b32_e32 v2, 0
	s_addc_u32 s63, s65, 0
	s_mov_b32 s31, 0
	v_mov_b32_e32 v3, v2
	v_mov_b32_e32 v4, v2
	v_mov_b32_e32 v5, v2
	v_mov_b32_e32 v6, v2
	v_mov_b32_e32 v7, v2
	v_mov_b32_e32 v8, v2
	v_mov_b32_e32 v9, v2
	v_mov_b32_e32 v10, v2
	v_mov_b32_e32 v11, v2
	v_mov_b32_e32 v12, v2
	v_mov_b32_e32 v13, v2
	v_mov_b32_e32 v18, v2
	v_mov_b32_e32 v19, v2
	v_mov_b32_e32 v20, v2
	v_mov_b32_e32 v21, v2
	v_mov_b32_e32 v26, v2
	v_mov_b32_e32 v27, v2
	v_mov_b32_e32 v28, v2
	v_mov_b32_e32 v29, v2
	v_mov_b32_e32 v34, v2
	v_mov_b32_e32 v35, v2
	v_mov_b32_e32 v36, v2
	v_mov_b32_e32 v37, v2
	v_mov_b32_e32 v42, v2
	v_mov_b32_e32 v43, v2
	v_mov_b32_e32 v44, v2
	v_mov_b32_e32 v45, v2
	v_mov_b32_e32 v50, v2
	v_mov_b32_e32 v51, v2
	v_mov_b32_e32 v52, v2
	v_mov_b32_e32 v53, v2
	v_mov_b32_e32 v14, v2
	v_mov_b32_e32 v15, v2
	v_mov_b32_e32 v16, v2
	v_mov_b32_e32 v17, v2
	v_mov_b32_e32 v22, v2
	v_mov_b32_e32 v23, v2
	v_mov_b32_e32 v24, v2
	v_mov_b32_e32 v25, v2
	v_mov_b32_e32 v30, v2
	v_mov_b32_e32 v31, v2
	v_mov_b32_e32 v32, v2
	v_mov_b32_e32 v33, v2
	v_mov_b32_e32 v38, v2
	v_mov_b32_e32 v39, v2
	v_mov_b32_e32 v40, v2
	v_mov_b32_e32 v41, v2
	v_mov_b32_e32 v46, v2
	v_mov_b32_e32 v47, v2
	v_mov_b32_e32 v48, v2
	v_mov_b32_e32 v49, v2
	v_mov_b32_e32 v54, v2
	v_mov_b32_e32 v55, v2
	v_mov_b32_e32 v56, v2
	v_mov_b32_e32 v57, v2
	v_mov_b32_e32 v58, v2
	v_mov_b32_e32 v59, v2
	v_mov_b32_e32 v60, v2
	v_mov_b32_e32 v61, v2
	v_mov_b32_e32 v62, v2
	v_mov_b32_e32 v63, v2
	v_mov_b32_e32 v64, v2
	v_mov_b32_e32 v65, v2
	v_mov_b32_e32 v66, v2
	v_mov_b32_e32 v67, v2
	v_mov_b32_e32 v68, v2
	v_mov_b32_e32 v69, v2
	v_mov_b32_e32 v70, v2
	v_mov_b32_e32 v71, v2
	v_mov_b32_e32 v72, v2
	v_mov_b32_e32 v73, v2
	v_mov_b32_e32 v74, v2
	v_mov_b32_e32 v75, v2
	v_mov_b32_e32 v76, v2
	v_mov_b32_e32 v77, v2
	v_mov_b32_e32 v78, v2
	v_mov_b32_e32 v79, v2
	v_mov_b32_e32 v80, v2
	v_mov_b32_e32 v81, v2
	v_mov_b32_e32 v90, v2
	v_mov_b32_e32 v91, v2
	v_mov_b32_e32 v92, v2
	v_mov_b32_e32 v93, v2
	v_mov_b32_e32 v94, v2
	v_mov_b32_e32 v95, v2
	v_mov_b32_e32 v96, v2
	v_mov_b32_e32 v97, v2
	v_mov_b32_e32 v106, v2
	v_mov_b32_e32 v107, v2
	v_mov_b32_e32 v108, v2
	v_mov_b32_e32 v109, v2
	v_mov_b32_e32 v110, v2
	v_mov_b32_e32 v111, v2
	v_mov_b32_e32 v112, v2
	v_mov_b32_e32 v113, v2
	v_mov_b32_e32 v82, v2
	v_mov_b32_e32 v83, v2
	v_mov_b32_e32 v84, v2
	v_mov_b32_e32 v85, v2
	v_mov_b32_e32 v86, v2
	v_mov_b32_e32 v87, v2
	v_mov_b32_e32 v88, v2
	v_mov_b32_e32 v89, v2
	v_mov_b32_e32 v98, v2
	v_mov_b32_e32 v99, v2
	v_mov_b32_e32 v100, v2
	v_mov_b32_e32 v101, v2
	v_mov_b32_e32 v102, v2
	v_mov_b32_e32 v103, v2
	v_mov_b32_e32 v104, v2
	v_mov_b32_e32 v105, v2
	v_mov_b32_e32 v114, v2
	v_mov_b32_e32 v115, v2
	v_mov_b32_e32 v116, v2
	v_mov_b32_e32 v117, v2
	v_mov_b32_e32 v118, v2
	v_mov_b32_e32 v119, v2
	v_mov_b32_e32 v120, v2
	v_mov_b32_e32 v121, v2
	v_mov_b32_e32 v122, v2
	v_mov_b32_e32 v123, v2
	v_mov_b32_e32 v124, v2
	v_mov_b32_e32 v125, v2
	v_mov_b32_e32 v126, v2
	v_mov_b32_e32 v127, v2
	v_mov_b32_e32 v128, v2
	v_mov_b32_e32 v129, v2
	.p2align 6
